# P0: the f32 w_in reads of the transpose are non-temporal too (read once)
# speedup vs baseline: 1.0209x; 1.0053x over previous
; __device__ __forceinline__ void p0_transpose_item(const float* __restrict__ W, int K, int N, bf16* __restrict__ WT, int mode, const float* __restrict__ kscale, int item, int lane) {
;     const int nblk = N / 64, kb = item / nblk, nb = item % nblk, k0 = 64 * kb, n0 = 64 * nb;
;     const float* src = W + (size_t)k0 * N + n0 + lane;
;     float v[64];
; #pragma unroll
;     for (int i = 0; i < 64; ++i) v[i] = src[(size_t)i * N];
; __global__ void __launch_bounds__(NWAVES * 64, 2) hybrid_fwd(Args args) {
;     ...
;         for (int it = gw; it < I_IN; it += NGW) p0_transpose_item(w_in, DM, NPROJ, Win_t, 0, nullptr, it, lane);
.LBB0_22:
	s_mul_hi_i32 s0, s65, 0x92492493
	s_add_i32 s0, s0, s65
	s_lshr_b32 s1, s0, 31
	s_ashr_i32 s0, s0, 6
	s_add_i32 s0, s0, s1
	s_mul_i32 s4, s0, 0xffffe400
	s_mul_i32 s5, s0, 0x1c0000
	s_lshl_b32 s0, s0, 6
	s_ashr_i32 s1, s0, 31
	s_add_i32 s4, s8, s4
	s_mul_hi_i32 s66, s0, 0x7000
	s_add_u32 s68, s84, s5
	s_addc_u32 s69, s85, s66
	s_ashr_i32 s5, s4, 31
	s_lshl_b64 s[66:67], s[4:5], 2
	s_add_u32 s66, s68, s66
	s_addc_u32 s67, s69, s67
	v_lshl_add_u64 v[2:3], s[66:67], 0, v[0:1]
	s_movk_i32 s5, 0x7000
	v_add_co_u32_e32 v4, vcc, s5, v2
	s_mov_b32 s5, 0x15000
	s_nop 0
	v_addc_co_u32_e32 v5, vcc, 0, v3, vcc
	v_add_co_u32_e32 v6, vcc, s5, v2
	s_mov_b32 s5, 0xe000
	s_nop 0
	v_addc_co_u32_e32 v7, vcc, 0, v3, vcc
	v_add_co_u32_e32 v8, vcc, s5, v2
	s_mov_b32 s5, 0x23000
	s_nop 0
	v_addc_co_u32_e32 v9, vcc, 0, v3, vcc
	v_add_co_u32_e32 v10, vcc, s5, v2
	s_mov_b32 s5, 0x1c000
	s_nop 0
	v_addc_co_u32_e32 v11, vcc, 0, v3, vcc
	v_add_co_u32_e32 v12, vcc, s5, v2
	s_mov_b32 s5, 0x31000
	s_nop 0
	v_addc_co_u32_e32 v13, vcc, 0, v3, vcc
	v_add_co_u32_e32 v14, vcc, s5, v2
	s_mov_b32 s5, 0x2a000
	s_nop 0
	v_addc_co_u32_e32 v15, vcc, 0, v3, vcc
	v_add_co_u32_e32 v16, vcc, s5, v2
	s_mov_b32 s5, 0x3f000
	s_nop 0
	v_addc_co_u32_e32 v17, vcc, 0, v3, vcc
	v_add_co_u32_e32 v18, vcc, s5, v2
	s_mov_b32 s5, 0x38000
	s_nop 0
	v_addc_co_u32_e32 v19, vcc, 0, v3, vcc
	v_add_co_u32_e32 v20, vcc, s5, v2
	s_mov_b32 s5, 0x4d000
	s_nop 0
	v_addc_co_u32_e32 v21, vcc, 0, v3, vcc
	v_add_co_u32_e32 v22, vcc, s5, v2
	s_mov_b32 s5, 0x46000
	s_nop 0
	v_addc_co_u32_e32 v23, vcc, 0, v3, vcc
	v_add_co_u32_e32 v24, vcc, s5, v2
	s_mov_b32 s5, 0x5b000
	s_nop 0
	v_addc_co_u32_e32 v25, vcc, 0, v3, vcc
	v_add_co_u32_e32 v26, vcc, s5, v2
	global_load_dword v52, v0, s[66:67] nt
	s_nop 0
	v_addc_co_u32_e32 v27, vcc, 0, v3, vcc
	v_add_co_u32_e32 v28, vcc, s12, v2
	s_add_i32 s65, s65, s78
	s_nop 0
	v_addc_co_u32_e32 v29, vcc, 0, v3, vcc
	v_add_co_u32_e32 v30, vcc, s13, v2
	s_add_i32 s8, s8, s9
	s_nop 0
	v_addc_co_u32_e32 v31, vcc, 0, v3, vcc
	v_add_co_u32_e32 v32, vcc, s14, v2
	s_cmpk_gt_i32 s65, 0xdff
	s_nop 0
	v_addc_co_u32_e32 v33, vcc, 0, v3, vcc
	v_add_co_u32_e32 v34, vcc, s15, v2
	s_nop 1
	v_addc_co_u32_e32 v35, vcc, 0, v3, vcc
	v_add_co_u32_e32 v36, vcc, s16, v2
	s_nop 1
	v_addc_co_u32_e32 v37, vcc, 0, v3, vcc
	v_add_co_u32_e32 v38, vcc, s17, v2
	s_nop 1
	v_addc_co_u32_e32 v39, vcc, 0, v3, vcc
	v_add_co_u32_e32 v40, vcc, s18, v2
	s_nop 1
	v_addc_co_u32_e32 v41, vcc, 0, v3, vcc
	v_add_co_u32_e32 v42, vcc, s19, v2
	s_nop 1
	v_addc_co_u32_e32 v43, vcc, 0, v3, vcc
	v_add_co_u32_e32 v44, vcc, s20, v2
	s_nop 1
	v_addc_co_u32_e32 v45, vcc, 0, v3, vcc
	v_add_co_u32_e32 v46, vcc, s21, v2
	s_nop 1
	v_addc_co_u32_e32 v47, vcc, 0, v3, vcc
	v_add_co_u32_e32 v48, vcc, s22, v2
	s_nop 1
	v_addc_co_u32_e32 v49, vcc, 0, v3, vcc
	v_add_co_u32_e32 v50, vcc, s23, v2
	s_nop 1
	v_addc_co_u32_e32 v51, vcc, 0, v3, vcc
	v_add_co_u32_e32 v54, vcc, s24, v2
	s_nop 1
	v_addc_co_u32_e32 v55, vcc, 0, v3, vcc
	v_add_co_u32_e32 v56, vcc, s25, v2
	s_nop 1
	v_addc_co_u32_e32 v57, vcc, 0, v3, vcc
	v_add_co_u32_e32 v58, vcc, s26, v2
	s_nop 1
	v_addc_co_u32_e32 v59, vcc, 0, v3, vcc
	v_add_co_u32_e32 v60, vcc, s27, v2
	s_nop 1
	v_addc_co_u32_e32 v61, vcc, 0, v3, vcc
	v_add_co_u32_e32 v62, vcc, s28, v2
	s_nop 1
	v_addc_co_u32_e32 v63, vcc, 0, v3, vcc
	v_add_co_u32_e32 v64, vcc, s29, v2
	s_nop 1
	v_addc_co_u32_e32 v65, vcc, 0, v3, vcc
	v_add_co_u32_e32 v66, vcc, s30, v2
	s_nop 1
	v_addc_co_u32_e32 v67, vcc, 0, v3, vcc
	v_add_co_u32_e32 v68, vcc, s31, v2
	s_nop 1
	v_addc_co_u32_e32 v69, vcc, 0, v3, vcc
	v_add_co_u32_e32 v70, vcc, s33, v2
	s_nop 1
	v_addc_co_u32_e32 v71, vcc, 0, v3, vcc
	v_add_co_u32_e32 v72, vcc, s34, v2
	s_nop 1
	v_addc_co_u32_e32 v73, vcc, 0, v3, vcc
	v_add_co_u32_e32 v74, vcc, s35, v2
	s_nop 1
	v_addc_co_u32_e32 v75, vcc, 0, v3, vcc
	v_add_co_u32_e32 v76, vcc, s36, v2
	s_nop 1
	v_addc_co_u32_e32 v77, vcc, 0, v3, vcc
	v_add_co_u32_e32 v78, vcc, s37, v2
	s_nop 1
	v_addc_co_u32_e32 v79, vcc, 0, v3, vcc
	v_add_co_u32_e32 v80, vcc, s38, v2
	s_nop 1
	v_addc_co_u32_e32 v81, vcc, 0, v3, vcc
	v_add_co_u32_e32 v82, vcc, s39, v2
	s_nop 1
	v_addc_co_u32_e32 v83, vcc, 0, v3, vcc
	v_add_co_u32_e32 v84, vcc, s40, v2
	s_nop 1
	v_addc_co_u32_e32 v85, vcc, 0, v3, vcc
	v_add_co_u32_e32 v86, vcc, s41, v2
	s_nop 1
	v_addc_co_u32_e32 v87, vcc, 0, v3, vcc
	v_add_co_u32_e32 v88, vcc, s42, v2
	s_nop 1
	v_addc_co_u32_e32 v89, vcc, 0, v3, vcc
	v_add_co_u32_e32 v90, vcc, s43, v2
	s_nop 1
	v_addc_co_u32_e32 v91, vcc, 0, v3, vcc
	v_add_co_u32_e32 v92, vcc, s44, v2
	s_nop 1
	v_addc_co_u32_e32 v93, vcc, 0, v3, vcc
	v_add_co_u32_e32 v94, vcc, s45, v2
	s_nop 1
	v_addc_co_u32_e32 v95, vcc, 0, v3, vcc
	v_add_co_u32_e32 v96, vcc, s46, v2
	s_nop 1
	v_addc_co_u32_e32 v97, vcc, 0, v3, vcc
	v_add_co_u32_e32 v98, vcc, s47, v2
	s_nop 1
	v_addc_co_u32_e32 v99, vcc, 0, v3, vcc
	v_add_co_u32_e32 v100, vcc, s48, v2
	s_nop 1
	v_addc_co_u32_e32 v101, vcc, 0, v3, vcc
	v_add_co_u32_e32 v102, vcc, s49, v2
	s_nop 1
	v_addc_co_u32_e32 v103, vcc, 0, v3, vcc
	v_add_co_u32_e32 v104, vcc, s51, v2
	s_nop 1
	v_addc_co_u32_e32 v105, vcc, 0, v3, vcc
	v_add_co_u32_e32 v106, vcc, s52, v2
	s_nop 1
	v_addc_co_u32_e32 v107, vcc, 0, v3, vcc
	v_add_co_u32_e32 v108, vcc, s53, v2
	s_nop 1
	v_addc_co_u32_e32 v109, vcc, 0, v3, vcc
	v_add_co_u32_e32 v110, vcc, s54, v2
	s_nop 1
	v_addc_co_u32_e32 v111, vcc, 0, v3, vcc
	v_add_co_u32_e32 v112, vcc, s55, v2
	s_nop 1
	v_addc_co_u32_e32 v113, vcc, 0, v3, vcc
	v_add_co_u32_e32 v114, vcc, s56, v2
	s_nop 1
	v_addc_co_u32_e32 v115, vcc, 0, v3, vcc
	v_add_co_u32_e32 v116, vcc, s57, v2
	s_nop 1
	v_addc_co_u32_e32 v117, vcc, 0, v3, vcc
; __device__ __forceinline__ unsigned cvtpk2(float lo, float hi) { unsigned r; asm volatile("v_cvt_pk_bf16_f32 %0, %1, %2" : "=v"(r) : "v"(lo), "v"(hi)); return r; }
; __device__ __forceinline__ void p0_transpose_item(const float* __restrict__ W, int K, int N, bf16* __restrict__ WT, int mode, const float* __restrict__ kscale, int item, int lane) {
;     ...
;     for (int i = 0; i < 64; ++i) v[i] = src[(size_t)i * N];
;     if (kscale) {
; #pragma unroll
;         for (int i = 0; i < 64; ++i) v[i] *= kscale[k0 + i]; }
;     const int rbase = (mode == 0) ? n0 : (256 * (n0 >> 7) + (n0 & 127) + (mode == 2 ? 128 : 0));
;     bf16* dst = WT + (size_t)(rbase + lane) * K + k0;
; #pragma unroll
;     for (int j = 0; j < 8; ++j) { v4u o; o.x = cvtpk2(v[8 * j], v[8 * j + 1]); o.y = cvtpk2(v[8 * j + 2], v[8 * j + 3]); o.z = cvtpk2(v[8 * j + 4], v[8 * j + 5]); o.w = cvtpk2(v[8 * j + 6], v[8 * j + 7]);
;         *(v4u*)(dst + 8 * j) = o; }
	v_add_co_u32_e32 v118, vcc, s58, v2
	s_nop 1
	v_addc_co_u32_e32 v119, vcc, 0, v3, vcc
	v_add_co_u32_e32 v120, vcc, s59, v2
	s_nop 1
	v_addc_co_u32_e32 v121, vcc, 0, v3, vcc
	v_add_co_u32_e32 v122, vcc, s60, v2
	s_nop 1
	v_addc_co_u32_e32 v123, vcc, 0, v3, vcc
	v_add_co_u32_e32 v124, vcc, s61, v2
	s_nop 1
	v_addc_co_u32_e32 v125, vcc, 0, v3, vcc
	v_add_co_u32_e32 v126, vcc, s62, v2
	s_nop 1
	v_addc_co_u32_e32 v127, vcc, 0, v3, vcc
	v_add_co_u32_e32 v128, vcc, s63, v2
	s_nop 1
	v_addc_co_u32_e32 v129, vcc, 0, v3, vcc
	v_add_co_u32_e32 v2, vcc, s64, v2
	s_nop 1
	v_addc_co_u32_e32 v3, vcc, 0, v3, vcc
	global_load_dword v4, v[4:5], off nt
	s_nop 0
	global_load_dword v5, v[6:7], off nt
	s_nop 0
	global_load_dword v8, v[8:9], off nt
	s_nop 0
	global_load_dword v9, v[10:11], off nt
	s_nop 0
	global_load_dword v10, v[12:13], off nt
	global_load_dword v11, v[14:15], off nt
	s_nop 0
	global_load_dword v12, v[16:17], off nt
	global_load_dword v13, v[18:19], off nt
	global_load_dword v14, v[20:21], off nt
	global_load_dword v15, v[22:23], off nt
	s_nop 0
	global_load_dword v16, v[24:25], off nt
	global_load_dword v17, v[26:27], off nt
	global_load_dword v18, v[28:29], off nt
	global_load_dword v19, v[30:31], off nt
	global_load_dword v20, v[32:33], off nt
	global_load_dword v21, v[34:35], off nt
	global_load_dword v22, v[36:37], off nt
	global_load_dword v23, v[38:39], off nt
	global_load_dword v24, v[40:41], off nt
	global_load_dword v25, v[42:43], off nt
	global_load_dword v26, v[44:45], off nt
	global_load_dword v27, v[46:47], off nt
	global_load_dword v28, v[48:49], off nt
	global_load_dword v29, v[50:51], off nt
	global_load_dword v30, v[54:55], off nt
	global_load_dword v31, v[56:57], off nt
	global_load_dword v32, v[58:59], off nt
	global_load_dword v33, v[60:61], off nt
	global_load_dword v34, v[62:63], off nt
	global_load_dword v35, v[64:65], off nt
	global_load_dword v36, v[66:67], off nt
	global_load_dword v37, v[68:69], off nt
	global_load_dword v38, v[70:71], off nt
	global_load_dword v39, v[72:73], off nt
	global_load_dword v40, v[74:75], off nt
	global_load_dword v41, v[76:77], off nt
	global_load_dword v42, v[78:79], off nt
	global_load_dword v43, v[80:81], off nt
	global_load_dword v44, v[82:83], off nt
	global_load_dword v45, v[84:85], off nt
	global_load_dword v46, v[86:87], off nt
	global_load_dword v47, v[88:89], off nt
	global_load_dword v48, v[90:91], off nt
	global_load_dword v49, v[92:93], off nt
	global_load_dword v50, v[94:95], off nt
	global_load_dword v51, v[96:97], off nt
	global_load_dword v53, v[98:99], off nt
	global_load_dword v54, v[100:101], off nt
	global_load_dword v55, v[102:103], off nt
	global_load_dword v56, v[104:105], off nt
	global_load_dword v57, v[106:107], off nt
	global_load_dword v58, v[108:109], off nt
	global_load_dword v59, v[110:111], off nt
	global_load_dword v60, v[112:113], off nt
	global_load_dword v61, v[114:115], off nt
	global_load_dword v62, v[116:117], off nt
	global_load_dword v63, v[118:119], off nt
	global_load_dword v64, v[120:121], off nt
	global_load_dword v65, v[122:123], off nt
	global_load_dword v66, v[124:125], off nt
	global_load_dword v67, v[126:127], off nt
	global_load_dword v68, v[128:129], off nt
	global_load_dword v69, v[2:3], off nt
	v_add_u32_e32 v2, s4, v184
	v_ashrrev_i32_e32 v3, 31, v2
	v_lshlrev_b64 v[2:3], 12, v[2:3]
	v_lshl_add_u64 v[2:3], s[10:11], 0, v[2:3]
	v_lshl_add_u64 v[6:7], s[0:1], 1, v[2:3]
	s_waitcnt vmcnt(62)
	v_cvt_pk_bf16_f32 v2, v52, v4
	s_waitcnt vmcnt(60)
	v_cvt_pk_bf16_f32 v3, v8, v5
	s_waitcnt vmcnt(58)
	v_cvt_pk_bf16_f32 v4, v10, v9
	s_waitcnt vmcnt(56)
	v_cvt_pk_bf16_f32 v5, v12, v11
	global_store_dwordx4 v[6:7], v[2:5], off
	s_waitcnt vmcnt(55)
	s_nop 0
	v_cvt_pk_bf16_f32 v2, v14, v13
	s_waitcnt vmcnt(53)
	v_cvt_pk_bf16_f32 v3, v16, v15
	s_waitcnt vmcnt(51)
	v_cvt_pk_bf16_f32 v4, v18, v17
	s_waitcnt vmcnt(49)
	v_cvt_pk_bf16_f32 v5, v20, v19
	global_store_dwordx4 v[6:7], v[2:5], off offset:16
	s_waitcnt vmcnt(48)
	s_nop 0
	v_cvt_pk_bf16_f32 v2, v22, v21
	s_waitcnt vmcnt(46)
	v_cvt_pk_bf16_f32 v3, v24, v23
	s_waitcnt vmcnt(44)
	v_cvt_pk_bf16_f32 v4, v26, v25
	s_waitcnt vmcnt(42)
	v_cvt_pk_bf16_f32 v5, v28, v27
	global_store_dwordx4 v[6:7], v[2:5], off offset:32
	s_waitcnt vmcnt(41)
	s_nop 0
	v_cvt_pk_bf16_f32 v2, v30, v29
	s_waitcnt vmcnt(39)
	v_cvt_pk_bf16_f32 v3, v32, v31
	s_waitcnt vmcnt(37)
	v_cvt_pk_bf16_f32 v4, v34, v33
	s_waitcnt vmcnt(35)
	v_cvt_pk_bf16_f32 v5, v36, v35
	global_store_dwordx4 v[6:7], v[2:5], off offset:48
	s_waitcnt vmcnt(34)
	s_nop 0
	v_cvt_pk_bf16_f32 v2, v38, v37
	s_waitcnt vmcnt(32)
	v_cvt_pk_bf16_f32 v3, v40, v39
	s_waitcnt vmcnt(30)
	v_cvt_pk_bf16_f32 v4, v42, v41
	s_waitcnt vmcnt(28)
	v_cvt_pk_bf16_f32 v5, v44, v43
	global_store_dwordx4 v[6:7], v[2:5], off offset:64
	s_waitcnt vmcnt(27)
	s_nop 0
	v_cvt_pk_bf16_f32 v2, v46, v45
	s_waitcnt vmcnt(25)
	v_cvt_pk_bf16_f32 v3, v48, v47
	s_waitcnt vmcnt(23)
	v_cvt_pk_bf16_f32 v4, v50, v49
	s_waitcnt vmcnt(21)
	v_cvt_pk_bf16_f32 v5, v53, v51
	global_store_dwordx4 v[6:7], v[2:5], off offset:80
	s_waitcnt vmcnt(20)
	s_nop 0
	v_cvt_pk_bf16_f32 v2, v55, v54
	s_waitcnt vmcnt(18)
	v_cvt_pk_bf16_f32 v3, v57, v56
	s_waitcnt vmcnt(16)
	v_cvt_pk_bf16_f32 v4, v59, v58
	s_waitcnt vmcnt(14)
	v_cvt_pk_bf16_f32 v5, v61, v60
	global_store_dwordx4 v[6:7], v[2:5], off offset:96
	s_waitcnt vmcnt(13)
	s_nop 0
	v_cvt_pk_bf16_f32 v2, v63, v62
	s_waitcnt vmcnt(11)
	v_cvt_pk_bf16_f32 v3, v65, v64
	s_waitcnt vmcnt(9)
	v_cvt_pk_bf16_f32 v4, v67, v66
	s_waitcnt vmcnt(7)
	v_cvt_pk_bf16_f32 v5, v69, v68
	global_store_dwordx4 v[6:7], v[2:5], off offset:112
	s_cbranch_scc0 .LBB0_22
